# combination: row-statistics prefetch build + attention step trims + no mid-block setprio flips + selected-block loop back edge shortened (pointer increments moved behind the prefetch loads)
# speedup vs baseline: 1.0111x; 1.0051x over previous
.LBB0_105:
	s_add_i32 s33, s33, 1
	s_addk_i32 s3, 0x4000
	s_cmp_eq_u32 s2, s33
	s_cbranch_scc1 .LBB0_120
.LBB0_106:
	s_and_b32 s4, s3, 0x4000
	s_add_i32 s45, s4, 0
	v_add_u32_e32 v50, s45, v133
	v_add_u32_e32 v51, v50, v134
	s_waitcnt vmcnt(1)
	ds_write_b128 v51, v[106:109] offset:49152
	v_add3_u32 v51, v50, v135, v136
	v_add3_u32 v50, v50, v137, v136
	s_waitcnt vmcnt(0)
	ds_write_b64 v51, v[102:103] offset:57344
	ds_write_b64 v50, v[104:105] offset:57344
	global_load_dwordx4 v[106:109], v[130:131], off
	global_load_dwordx4 v[102:105], v[128:129], off
	v_lshl_add_u64 v[128:129], v[128:129], 0, s[34:35]
	v_lshl_add_u64 v[130:131], v[130:131], 0, s[26:27]
	v_lshrrev_b32_e32 v50, s33, v142
	v_and_b32_e32 v50, 1, v50
	v_cmp_eq_u32_e64 s[38:39], 1, v50
	v_bfe_u32 v50, v142, s33, 1
	s_andn2_b64 s[4:5], s[0:1], exec
	s_and_b64 s[40:41], s[0:1], exec
	v_cmp_ne_u32_e32 vcc, 0, v50
	s_or_b64 s[4:5], s[4:5], s[40:41]
	s_waitcnt lgkmcnt(0)
	s_barrier
	s_cbranch_vccz .LBB0_104
	v_add_u32_e32 v50, s45, v0
	s_mov_b32 s44, 0x7f800000
	v_add_u32_e32 v146, v50, v138
	ds_read_b128 v[66:69], v146 offset:49152
	v_add_u32_e32 v147, v50, v139
	ds_read_b128 v[110:113], v147 offset:49152
	v_add_u32_e32 v144, v50, v140
	ds_read_b128 v[114:117], v144 offset:49152
	v_add_u32_e32 v145, v50, v141
	ds_read_b128 v[118:121], v145 offset:49152
	ds_read_b128 v[122:125], v146 offset:53248
	ds_read_b128 v[148:151], v147 offset:53248
	ds_read_b128 v[152:155], v144 offset:53248
	ds_read_b128 v[156:159], v145 offset:53248
	s_waitcnt lgkmcnt(7)
	v_mfma_f32_32x32x16_bf16 v[50:65], v[66:69], v[98:101], v[34:49]
	s_waitcnt lgkmcnt(6)
	v_mfma_f32_32x32x16_bf16 v[50:65], v[110:113], v[86:89], v[50:65]
	s_cmp_lg_u64 vcc, -1
	s_cselect_b64 s[40:41], -1, 0
	s_cmp_eq_u64 vcc, -1
	s_cselect_b64 s[42:43], -1, 0
	s_or_b64 vcc, s[42:43], s[38:39]
	s_waitcnt lgkmcnt(3)
	v_mfma_f32_32x32x16_bf16 v[66:81], v[122:125], v[98:101], v[34:49]
	s_waitcnt lgkmcnt(2)
	v_mfma_f32_32x32x16_bf16 v[66:81], v[148:151], v[86:89], v[66:81]
	v_mfma_f32_32x32x16_bf16 v[50:65], v[114:117], v[82:85], v[50:65]
	s_waitcnt lgkmcnt(1)
	v_mfma_f32_32x32x16_bf16 v[66:81], v[152:155], v[82:85], v[66:81]
	v_mfma_f32_32x32x16_bf16 v[50:65], v[118:121], v[90:93], v[50:65]
	ds_read_b128 v[114:117], v146 offset:57344
	ds_read_b128 v[110:113], v147 offset:57344
	ds_read_b128 v[118:121], v144 offset:57344
	ds_read_b128 v[122:125], v145 offset:57344
	s_waitcnt lgkmcnt(4)
	v_mfma_f32_32x32x16_bf16 v[66:81], v[156:159], v[90:93], v[66:81]
	s_nop 5
	v_max3_f32 v149, v50, v51, v52
	v_max3_f32 v149, v149, v53, v54
	v_max3_f32 v149, v149, v55, v56
	v_max3_f32 v149, v149, v57, v58
	v_max3_f32 v149, v149, v59, v60
	v_max3_f32 v149, v149, v61, v62
	v_max3_f32 v149, v149, v63, v64
	v_max3_f32 v150, v66, v67, v68
	v_max3_f32 v150, v150, v69, v70
	v_max3_f32 v150, v150, v71, v72
	v_max3_f32 v150, v150, v73, v74
	v_max3_f32 v150, v150, v75, v76
	v_max3_f32 v150, v150, v77, v78
	v_max3_f32 v150, v150, v79, v80
	v_max3_f32 v148, v149, v150, v65
	v_max_f32_e32 v148, v148, v81
	v_cndmask_b32_e32 v148, v225, v148, vcc
	v_mov_b32_e32 v149, v148
	s_nop 1
	v_permlane32_swap_b32_e32 v148, v149
	v_max_f32_e32 v148, v148, v149
	v_cndmask_b32_e64 v149, v227, v228, s[0:1]
	v_cmp_gt_f32_e32 vcc, v148, v149
	s_cbranch_vccz .LBB0_109
	s_nop 0
	v_cndmask_b32_e32 v36, 0, v148, vcc
	v_exp_f32_e64 v38, -v36
	v_add_f32_e32 v143, v143, v36
	v_xor_b32_e32 v34, 0x80000000, v143
	v_pk_add_f32 v[50:51], v[50:51], v[36:37] op_sel_hi:[1,0] neg_lo:[0,1] neg_hi:[0,1]
	v_mul_f32_e32 v127, v127, v38
	v_pk_add_f32 v[66:67], v[66:67], v[36:37] op_sel_hi:[1,0] neg_lo:[0,1] neg_hi:[0,1]
	v_pk_add_f32 v[52:53], v[52:53], v[36:37] op_sel_hi:[1,0] neg_lo:[0,1] neg_hi:[0,1]
	v_pk_add_f32 v[68:69], v[68:69], v[36:37] op_sel_hi:[1,0] neg_lo:[0,1] neg_hi:[0,1]
	v_pk_add_f32 v[54:55], v[54:55], v[36:37] op_sel_hi:[1,0] neg_lo:[0,1] neg_hi:[0,1]
	v_pk_add_f32 v[70:71], v[70:71], v[36:37] op_sel_hi:[1,0] neg_lo:[0,1] neg_hi:[0,1]
	v_pk_add_f32 v[56:57], v[56:57], v[36:37] op_sel_hi:[1,0] neg_lo:[0,1] neg_hi:[0,1]
	v_pk_add_f32 v[72:73], v[72:73], v[36:37] op_sel_hi:[1,0] neg_lo:[0,1] neg_hi:[0,1]
	v_pk_add_f32 v[58:59], v[58:59], v[36:37] op_sel_hi:[1,0] neg_lo:[0,1] neg_hi:[0,1]
	v_pk_add_f32 v[74:75], v[74:75], v[36:37] op_sel_hi:[1,0] neg_lo:[0,1] neg_hi:[0,1]
	v_pk_add_f32 v[60:61], v[60:61], v[36:37] op_sel_hi:[1,0] neg_lo:[0,1] neg_hi:[0,1]
	v_pk_add_f32 v[76:77], v[76:77], v[36:37] op_sel_hi:[1,0] neg_lo:[0,1] neg_hi:[0,1]
	v_pk_add_f32 v[62:63], v[62:63], v[36:37] op_sel_hi:[1,0] neg_lo:[0,1] neg_hi:[0,1]
	v_pk_add_f32 v[78:79], v[78:79], v[36:37] op_sel_hi:[1,0] neg_lo:[0,1] neg_hi:[0,1]
	v_pk_mul_f32 v[16:17], v[16:17], v[38:39] op_sel_hi:[1,0]
	v_pk_mul_f32 v[14:15], v[14:15], v[38:39] op_sel_hi:[1,0]
	v_pk_mul_f32 v[12:13], v[12:13], v[38:39] op_sel_hi:[1,0]
	v_pk_mul_f32 v[10:11], v[10:11], v[38:39] op_sel_hi:[1,0]
	v_pk_mul_f32 v[8:9], v[8:9], v[38:39] op_sel_hi:[1,0]
	v_pk_mul_f32 v[6:7], v[6:7], v[38:39] op_sel_hi:[1,0]
	v_pk_mul_f32 v[4:5], v[4:5], v[38:39] op_sel_hi:[1,0]
	v_pk_mul_f32 v[2:3], v[2:3], v[38:39] op_sel_hi:[1,0]
	v_pk_mul_f32 v[32:33], v[32:33], v[38:39] op_sel_hi:[1,0]
	v_pk_mul_f32 v[30:31], v[30:31], v[38:39] op_sel_hi:[1,0]
	v_pk_mul_f32 v[28:29], v[28:29], v[38:39] op_sel_hi:[1,0]
	v_pk_mul_f32 v[26:27], v[26:27], v[38:39] op_sel_hi:[1,0]
	v_pk_mul_f32 v[24:25], v[24:25], v[38:39] op_sel_hi:[1,0]
	v_pk_mul_f32 v[22:23], v[22:23], v[38:39] op_sel_hi:[1,0]
	v_pk_mul_f32 v[20:21], v[20:21], v[38:39] op_sel_hi:[1,0]
	v_pk_mul_f32 v[18:19], v[18:19], v[38:39] op_sel_hi:[1,0]
	v_pk_add_f32 v[64:65], v[64:65], v[36:37] op_sel_hi:[1,0] neg_lo:[0,1] neg_hi:[0,1]
	v_pk_add_f32 v[80:81], v[80:81], v[36:37] op_sel_hi:[1,0] neg_lo:[0,1] neg_hi:[0,1]
	v_mov_b32_e32 v35, v34
	v_mov_b32_e32 v36, v34
	v_mov_b32_e32 v37, v34
	v_mov_b32_e32 v38, v34
	v_mov_b32_e32 v39, v34
	v_mov_b32_e32 v40, v34
	v_mov_b32_e32 v41, v34
	v_mov_b32_e32 v42, v34
	v_mov_b32_e32 v43, v34
	v_mov_b32_e32 v44, v34
	v_mov_b32_e32 v45, v34
	v_mov_b32_e32 v46, v34
	v_mov_b32_e32 v47, v34
	v_mov_b32_e32 v48, v34
	v_mov_b32_e32 v49, v34
